# attention: first K-fragment LDS reads issued right behind the tile barrier (latency overlaps scalar tile logic)
# speedup vs baseline: 1.0116x; 1.0116x over previous
; template <int MODE> ...
;     ...
;   for (int it = 0; it < ntile; ++it) {
;     const int kt0 = (it < na) ? ka0 + it * 64 : kb0 + (it - na) * 64;
;     const bool masked = window && (it < na);
;     const u16* Ks = Kbase + (it & 1) * (2 * 64 * 64);
;     const u16* Vs = Ks + 64 * 64;
;     __syncthreads();
;     const bool more = it + 1 < ntile;
;     if (more) {
;       const int kn = (it + 1 < na) ? ka0 + (it + 1) * 64 : kb0 + (it + 1 - na) * 64;
;       ALOAD(kn)
;     }
;     ...
;     for (int kh = 0; kh < 2; ++kh) {
;       bf16x8 kf[2][2];
; #pragma unroll
;       for (int t = 0; t < 2; ++t)
; #pragma unroll
;         for (int s2 = 0; s2 < 2; ++s2)
;           kf[t][s2] = *(const bf16x8*)&Ks[(kh * 32 + t * 16 + r) * 64 + (((s2 * 4 + g) ^ (r & 7)) * 8)];
.LBB0_862:
	s_add_i32 s66, s58, 1
	s_cmp_lt_i32 s66, s45
	s_cselect_b64 s[56:57], -1, 0
	s_waitcnt lgkmcnt(0)
	s_barrier
	s_add_i32 s98, s2, 0xffffe000
	s_and_b32 s98, s98, 0x2000
	v_lshl_add_u32 v0, s98, 1, v233
	v_add_u32_e32 v234, v0, v230
	v_add_u32_e32 v0, v0, v231
	ds_read_b128 v[108:111], v234
	ds_read_b128 v[112:115], v234 offset:2048
	ds_read_b128 v[120:123], v0
	ds_read_b128 v[132:135], v0 offset:2048
	s_cmp_ge_i32 s66, s45
	s_cbranch_scc1 .LBB0_864
	s_cmp_lt_i32 s66, s63
	s_cselect_b32 s59, 0, s63
	s_cselect_b32 s60, s64, 0x800
	s_lshl_b32 s59, s59, 6
	s_sub_i32 s59, s60, s59
	s_add_i32 s60, s65, s59
	s_ashr_i32 s61, s60, 31
	s_lshl_b64 s[68:69], s[60:61], 7
	s_waitcnt vmcnt(1)
	v_lshl_add_u64 v[100:101], v[182:183], 0, s[68:69]
	s_waitcnt vmcnt(0)
	v_lshl_add_u64 v[104:105], s[60:61], 1, v[184:185]
	global_load_dwordx4 v[100:103], v[100:101], off
	s_nop 0
	global_load_dwordx4 v[104:107], v[104:105], off

; template <int MODE> ...
;     ...
;     const bool more = it + 1 < ntile;
;     if (more) {
;       const int kn = (it + 1 < na) ? ka0 + (it + 1) * 64 : kb0 + (it + 1 - na) * 64;
;       ALOAD(kn)
;     }
;     bool skip = false;
;     if (masked) {
;       const int qlo = qtok0 + __builtin_amdgcn_readfirstlane(w) * 32;
;       skip = (kt0 > qlo + 31 + 128) || (kt0 + 63 < qlo - 128);
;     }
;     if (!skip) {
.LBB0_866:
	s_waitcnt lgkmcnt(0)
	s_andn2_b64 vcc, exec, s[56:57]
	s_cbranch_vccnz .LBB0_874

; #define MFMA(a, b, c) __builtin_amdgcn_mfma_f32_16x16x32_bf16((a), (b), (c), 0, 0, 0)
; template <int MODE> ...
;     ...
;     for (int kh = 0; kh < 2; ++kh) {
;       bf16x8 kf[2][2];
; #pragma unroll
;       for (int t = 0; t < 2; ++t)
; #pragma unroll
;         for (int s2 = 0; s2 < 2; ++s2)
;           kf[t][s2] = *(const bf16x8*)&Ks[(kh * 32 + t * 16 + r) * 64 + (((s2 * 4 + g) ^ (r & 7)) * 8)];
; #pragma unroll
;       for (int tt = 0; tt < 2; ++tt)
; #pragma unroll
;         for (int hh = 0; hh < 2; ++hh) {
;           f32x4 s0 = zero4(), s1 = zero4();
;           if constexpr (MODE == 0) {
;             s0 = MFMA(kf[0][0], qf[tt][hh][0], s0);
;             s1 = MFMA(kf[1][0], qf[tt][hh][0], s1);
;             s0 = MFMA(kf[0][1], qf[tt][hh][1], s0);
;             s1 = MFMA(kf[1][1], qf[tt][hh][1], s1);
;           } else {
;             s0 = MFMA(kf[0][hh], qf[tt][hh][0], s0);
;             s1 = MFMA(kf[1][hh], qf[tt][hh][0], s1);
;           }
;           S[kh][tt][hh][0] = s0;
;           S[kh][tt][hh][1] = s1;
;         }
;     }
;     if (masked) {
; #pragma unroll
;       for (int kh = 0; kh < 2; ++kh)
; #pragma unroll
;         for (int tt = 0; tt < 2; ++tt) {
;           const int qpos = qtok0 + w * 32 + tt * 16 + r;
;           const int kp0 = kt0 + kh * 32 + g * 8;
; #pragma unroll
;           for (int t = 0; t < 2; ++t)
; #pragma unroll
;             for (int j = 0; j < 4; ++j) {
;               int d = kp0 + t * 4 + j - qpos;
;               d = d < 0 ? -d : d;
;               if (d > 128) { S[kh][tt][0][t][j] = -INFINITY; S[kh][tt][1][t][j] = -INFINITY; }
;             }
;         }
.LBB0_869:
	s_waitcnt lgkmcnt(3)
	v_mfma_f32_16x16x32_bf16 v[116:119], v[108:111], v[68:71], 0
	ds_read_b128 v[190:193], v0 offset:4096
	ds_read_b128 v[196:199], v0 offset:6144
	s_andn2_b64 vcc, exec, s[58:59]
	s_waitcnt lgkmcnt(4)
	v_mfma_f32_16x16x32_bf16 v[124:127], v[112:115], v[68:71], 0
	s_waitcnt lgkmcnt(3)
	v_mfma_f32_16x16x32_bf16 v[160:163], v[120:123], v[72:75], v[116:119]
	v_mfma_f32_16x16x32_bf16 v[116:119], v[108:111], v[76:79], 0
	s_waitcnt lgkmcnt(2)
	v_mfma_f32_16x16x32_bf16 v[156:159], v[132:135], v[72:75], v[124:127]
	v_mfma_f32_16x16x32_bf16 v[124:127], v[112:115], v[76:79], 0
	v_mfma_f32_16x16x32_bf16 v[144:147], v[120:123], v[80:83], v[116:119]
	v_mfma_f32_16x16x32_bf16 v[116:119], v[108:111], v[84:87], 0
	v_mfma_f32_16x16x32_bf16 v[108:111], v[108:111], v[92:95], 0
	v_mfma_f32_16x16x32_bf16 v[140:143], v[132:135], v[80:83], v[124:127]
	v_mfma_f32_16x16x32_bf16 v[124:127], v[112:115], v[84:87], 0
	v_mfma_f32_16x16x32_bf16 v[128:131], v[120:123], v[88:91], v[116:119]
	v_mfma_f32_16x16x32_bf16 v[116:119], v[112:115], v[92:95], 0
	v_mfma_f32_16x16x32_bf16 v[112:115], v[120:123], v[96:99], v[108:111]
	ds_read_b128 v[120:123], v234 offset:4096
	v_mfma_f32_16x16x32_bf16 v[108:111], v[132:135], v[96:99], v[116:119]
	s_nop 4
	ds_read_b128 v[116:119], v234 offset:6144
	v_mfma_f32_16x16x32_bf16 v[124:127], v[132:135], v[88:91], v[124:127]
	s_waitcnt lgkmcnt(1)
	v_mfma_f32_16x16x32_bf16 v[132:135], v[120:123], v[68:71], 0
	s_waitcnt lgkmcnt(0)
	v_mfma_f32_16x16x32_bf16 v[136:139], v[116:119], v[68:71], 0
	v_mfma_f32_16x16x32_bf16 v[168:171], v[190:193], v[72:75], v[132:135]
	v_mfma_f32_16x16x32_bf16 v[132:135], v[120:123], v[76:79], 0
	v_mfma_f32_16x16x32_bf16 v[164:167], v[196:199], v[72:75], v[136:139]
	v_mfma_f32_16x16x32_bf16 v[136:139], v[116:119], v[76:79], 0
	v_mfma_f32_16x16x32_bf16 v[152:155], v[190:193], v[80:83], v[132:135]
	v_mfma_f32_16x16x32_bf16 v[132:135], v[120:123], v[84:87], 0
	v_mfma_f32_16x16x32_bf16 v[200:203], v[116:119], v[84:87], 0
	v_mfma_f32_16x16x32_bf16 v[120:123], v[120:123], v[92:95], 0
	v_mfma_f32_16x16x32_bf16 v[116:119], v[116:119], v[92:95], 0
	v_mfma_f32_16x16x32_bf16 v[148:151], v[196:199], v[80:83], v[136:139]
	v_mfma_f32_16x16x32_bf16 v[136:139], v[190:193], v[88:91], v[132:135]
	v_mfma_f32_16x16x32_bf16 v[132:135], v[196:199], v[88:91], v[200:203]
	v_mfma_f32_16x16x32_bf16 v[120:123], v[190:193], v[96:99], v[120:123]
	v_mfma_f32_16x16x32_bf16 v[116:119], v[196:199], v[96:99], v[116:119]
	s_cbranch_vccnz .LBB0_871
	s_add_i32 s67, s67, s65
	v_add_u32_e32 v191, s67, v232
	v_subrev_u32_e32 v190, 64, v191
	v_sub_u32_e32 v192, 64, v191
	v_max_i32_e32 v193, v190, v192
	v_mov_b32_e32 v190, s20
	v_mov_b32_e32 v192, s20
	v_cmp_lt_u32_e32 vcc, s95, v193
	s_nop 1
	v_cndmask_b32_e32 v144, v144, v192, vcc
	v_cndmask_b32_e32 v160, v160, v190, vcc
	v_subrev_u32_e32 v190, 63, v191
	v_sub_u32_e32 v192, 63, v191
	v_max_i32_e32 v190, v190, v192
	v_cmp_lt_u32_e32 vcc, s95, v190
	v_subrev_u32_e32 v190, 62, v191
	v_sub_u32_e32 v192, 62, v191
	v_max_i32_e32 v190, v190, v192
	v_cndmask_b32_e32 v145, v145, v194, vcc
	v_cndmask_b32_e32 v161, v161, v194, vcc
	v_cmp_lt_u32_e32 vcc, s95, v190
	v_subrev_u32_e32 v190, 61, v191
	v_sub_u32_e32 v192, 61, v191
	v_max_i32_e32 v190, v190, v192
	v_cndmask_b32_e32 v146, v146, v194, vcc
	v_cndmask_b32_e32 v162, v162, v194, vcc
	v_cmp_lt_u32_e32 vcc, s95, v190
	v_subrev_u32_e32 v190, 60, v191
	v_sub_u32_e32 v192, 60, v191
	v_max_i32_e32 v193, v190, v192
	v_cndmask_b32_e32 v147, v147, v194, vcc
	v_cndmask_b32_e32 v163, v163, v194, vcc
	v_mov_b32_e32 v190, s20
	v_mov_b32_e32 v192, s20
	v_cmp_lt_u32_e32 vcc, s95, v193
	s_nop 1
	v_cndmask_b32_e32 v140, v140, v192, vcc
	v_cndmask_b32_e32 v156, v156, v190, vcc
	v_subrev_u32_e32 v190, 59, v191
	v_sub_u32_e32 v192, 59, v191
	v_max_i32_e32 v190, v190, v192
	v_cmp_lt_u32_e32 vcc, s95, v190
	v_subrev_u32_e32 v190, 58, v191
	v_sub_u32_e32 v192, 58, v191
	v_max_i32_e32 v190, v190, v192
	v_cndmask_b32_e32 v141, v141, v194, vcc
	v_cndmask_b32_e32 v157, v157, v194, vcc
	v_cmp_lt_u32_e32 vcc, s95, v190
	v_subrev_u32_e32 v190, 57, v191
	v_sub_u32_e32 v192, 57, v191
	v_max_i32_e32 v190, v190, v192
	v_cndmask_b32_e32 v142, v142, v194, vcc
	v_cndmask_b32_e32 v158, v158, v194, vcc
	v_cmp_lt_u32_e32 vcc, s95, v190
	v_add_u32_e32 v190, 0xffffffb0, v191
	v_sub_u32_e32 v192, 0x50, v191
	v_max_i32_e32 v193, v190, v192
	v_cndmask_b32_e32 v143, v143, v194, vcc
	v_cndmask_b32_e32 v159, v159, v194, vcc
	v_mov_b32_e32 v190, s20
	v_mov_b32_e32 v192, s20
	v_cmp_lt_u32_e32 vcc, s95, v193
	s_nop 1
	v_cndmask_b32_e32 v112, v112, v192, vcc
	v_cndmask_b32_e32 v128, v128, v190, vcc
	v_add_u32_e32 v190, 0xffffffb1, v191
	v_sub_u32_e32 v192, 0x4f, v191
	v_max_i32_e32 v190, v190, v192
	v_cmp_lt_u32_e32 vcc, s95, v190
	v_add_u32_e32 v190, 0xffffffb2, v191
	v_sub_u32_e32 v192, 0x4e, v191
	v_max_i32_e32 v190, v190, v192
	v_cndmask_b32_e32 v113, v113, v194, vcc
; template <int MODE> ...
;     ...
;     if (masked) {
; #pragma unroll
;       for (int kh = 0; kh < 2; ++kh)
; #pragma unroll
;         for (int tt = 0; tt < 2; ++tt) {
;           const int qpos = qtok0 + w * 32 + tt * 16 + r;
;           const int kp0 = kt0 + kh * 32 + g * 8;
; #pragma unroll
;           for (int t = 0; t < 2; ++t)
; #pragma unroll
;             for (int j = 0; j < 4; ++j) {
;               int d = kp0 + t * 4 + j - qpos;
;               d = d < 0 ? -d : d;
;               if (d > 128) { S[kh][tt][0][t][j] = -INFINITY; S[kh][tt][1][t][j] = -INFINITY; }
;             }
;         }
	v_cndmask_b32_e32 v129, v129, v194, vcc
	v_cmp_lt_u32_e32 vcc, s95, v190
	v_add_u32_e32 v190, 0xffffffb3, v191
	v_sub_u32_e32 v192, 0x4d, v191
	v_max_i32_e32 v190, v190, v192
	v_cndmask_b32_e32 v114, v114, v194, vcc
	v_cndmask_b32_e32 v130, v130, v194, vcc
	v_cmp_lt_u32_e32 vcc, s95, v190
	v_add_u32_e32 v190, 0xffffffb4, v191
	v_sub_u32_e32 v192, 0x4c, v191
	v_max_i32_e32 v193, v190, v192
	v_cndmask_b32_e32 v115, v115, v194, vcc
	v_cndmask_b32_e32 v131, v131, v194, vcc
	v_mov_b32_e32 v190, s20
	v_mov_b32_e32 v192, s20
	v_cmp_lt_u32_e32 vcc, s95, v193
	s_nop 1
	v_cndmask_b32_e32 v108, v108, v192, vcc
	v_cndmask_b32_e32 v124, v124, v190, vcc
	v_add_u32_e32 v190, 0xffffffb5, v191
	v_sub_u32_e32 v192, 0x4b, v191
	v_max_i32_e32 v190, v190, v192
	v_cmp_lt_u32_e32 vcc, s95, v190
	v_add_u32_e32 v190, 0xffffffb6, v191
	v_sub_u32_e32 v192, 0x4a, v191
	v_max_i32_e32 v190, v190, v192
	v_cndmask_b32_e32 v109, v109, v194, vcc
	v_cndmask_b32_e32 v125, v125, v194, vcc
	v_cmp_lt_u32_e32 vcc, s95, v190
	v_add_u32_e32 v190, 0xffffffb7, v191
	v_sub_u32_e32 v192, 0x49, v191
	v_max_i32_e32 v190, v190, v192
	v_cndmask_b32_e32 v110, v110, v194, vcc
	v_cndmask_b32_e32 v126, v126, v194, vcc
	v_cmp_lt_u32_e32 vcc, s95, v190
	v_subrev_u32_e32 v190, 32, v191
	v_sub_u32_e32 v192, 32, v191
	v_max_i32_e32 v193, v190, v192
	v_cndmask_b32_e32 v111, v111, v194, vcc
	v_cndmask_b32_e32 v127, v127, v194, vcc
	v_mov_b32_e32 v190, s20
	v_mov_b32_e32 v192, s20
	v_cmp_lt_u32_e32 vcc, s95, v193
	s_nop 1
	v_cndmask_b32_e32 v152, v152, v192, vcc
	v_cndmask_b32_e32 v168, v168, v190, vcc
	v_subrev_u32_e32 v190, 31, v191
	v_sub_u32_e32 v192, 31, v191
	v_max_i32_e32 v190, v190, v192
	v_cmp_lt_u32_e32 vcc, s95, v190
	v_subrev_u32_e32 v190, 30, v191
	v_sub_u32_e32 v192, 30, v191
	v_max_i32_e32 v190, v190, v192
	v_cndmask_b32_e32 v153, v153, v194, vcc
	v_cndmask_b32_e32 v169, v169, v194, vcc
	v_cmp_lt_u32_e32 vcc, s95, v190
	v_subrev_u32_e32 v190, 29, v191
	v_sub_u32_e32 v192, 29, v191
	v_max_i32_e32 v190, v190, v192
	v_cndmask_b32_e32 v154, v154, v194, vcc
	v_cndmask_b32_e32 v170, v170, v194, vcc
	v_cmp_lt_u32_e32 vcc, s95, v190
	v_subrev_u32_e32 v190, 28, v191
	v_sub_u32_e32 v192, 28, v191
	v_max_i32_e32 v193, v190, v192
	v_cndmask_b32_e32 v155, v155, v194, vcc
	v_cndmask_b32_e32 v171, v171, v194, vcc
	v_mov_b32_e32 v190, s20
	v_mov_b32_e32 v192, s20
	v_cmp_lt_u32_e32 vcc, s95, v193
	s_nop 1
	v_cndmask_b32_e32 v148, v148, v192, vcc
	v_cndmask_b32_e32 v164, v164, v190, vcc
	v_subrev_u32_e32 v190, 27, v191
	v_sub_u32_e32 v192, 27, v191
	v_max_i32_e32 v190, v190, v192
	v_cmp_lt_u32_e32 vcc, s95, v190
	v_subrev_u32_e32 v190, 26, v191
	v_sub_u32_e32 v192, 26, v191
	v_max_i32_e32 v190, v190, v192
	v_cndmask_b32_e32 v149, v149, v194, vcc
	v_cndmask_b32_e32 v165, v165, v194, vcc
	v_cmp_lt_u32_e32 vcc, s95, v190
	v_subrev_u32_e32 v190, 25, v191
	v_sub_u32_e32 v192, 25, v191
	v_max_i32_e32 v190, v190, v192
	v_cndmask_b32_e32 v150, v150, v194, vcc
	v_cndmask_b32_e32 v166, v166, v194, vcc
	v_cmp_lt_u32_e32 vcc, s95, v190
	v_subrev_u32_e32 v190, 48, v191
	v_sub_u32_e32 v192, 48, v191
	v_max_i32_e32 v193, v190, v192
	v_cndmask_b32_e32 v151, v151, v194, vcc
	v_cndmask_b32_e32 v167, v167, v194, vcc
	v_mov_b32_e32 v190, s20
	v_mov_b32_e32 v192, s20
	v_cmp_lt_u32_e32 vcc, s95, v193
	s_nop 1
	v_cndmask_b32_e32 v120, v120, v192, vcc
	v_cndmask_b32_e32 v136, v136, v190, vcc
	v_subrev_u32_e32 v190, 47, v191
	v_sub_u32_e32 v192, 47, v191
	v_max_i32_e32 v190, v190, v192
	v_cmp_lt_u32_e32 vcc, s95, v190
	v_subrev_u32_e32 v190, 46, v191
	v_sub_u32_e32 v192, 46, v191
	v_max_i32_e32 v190, v190, v192
	v_cndmask_b32_e32 v121, v121, v194, vcc
	v_cndmask_b32_e32 v137, v137, v194, vcc
	v_cmp_lt_u32_e32 vcc, s95, v190
	v_subrev_u32_e32 v190, 45, v191
	v_sub_u32_e32 v192, 45, v191
	v_max_i32_e32 v190, v190, v192
	v_cndmask_b32_e32 v122, v122, v194, vcc
	v_cndmask_b32_e32 v138, v138, v194, vcc
	v_cmp_lt_u32_e32 vcc, s95, v190
	v_subrev_u32_e32 v190, 44, v191
	v_sub_u32_e32 v192, 44, v191
	v_max_i32_e32 v193, v190, v192
	v_cndmask_b32_e32 v123, v123, v194, vcc
	v_cndmask_b32_e32 v139, v139, v194, vcc
	v_mov_b32_e32 v190, s20
	v_mov_b32_e32 v192, s20
	v_cmp_lt_u32_e32 vcc, s95, v193
	s_nop 1
	v_cndmask_b32_e32 v116, v116, v192, vcc
	v_cndmask_b32_e32 v132, v132, v190, vcc
	v_subrev_u32_e32 v190, 43, v191
	v_sub_u32_e32 v192, 43, v191
	v_max_i32_e32 v190, v190, v192
	v_cmp_lt_u32_e32 vcc, s95, v190
	v_subrev_u32_e32 v190, 42, v191
	v_sub_u32_e32 v192, 42, v191
	v_max_i32_e32 v190, v190, v192
	v_cndmask_b32_e32 v117, v117, v194, vcc
	v_cndmask_b32_e32 v133, v133, v194, vcc
	v_cmp_lt_u32_e32 vcc, s95, v190
	v_subrev_u32_e32 v190, 41, v191
	v_sub_u32_e32 v191, 41, v191
	v_max_i32_e32 v190, v190, v191
	v_cndmask_b32_e32 v118, v118, v194, vcc
	v_cndmask_b32_e32 v134, v134, v194, vcc
	v_cmp_lt_u32_e32 vcc, s95, v190
	s_nop 1
	v_cndmask_b32_e32 v119, v119, v194, vcc
	v_cndmask_b32_e32 v135, v135, v194, vcc

; template <int MODE> ...
;     ...
;   for (int it = 0; it < ntile; ++it) {
;     const int kt0 = (it < na) ? ka0 + it * 64 : kb0 + (it - na) * 64;
;     const bool masked = window && (it < na);
;     const u16* Ks = Kbase + (it & 1) * (2 * 64 * 64);
;     const u16* Vs = Ks + 64 * 64;
;     __syncthreads();
;     const bool more = it + 1 < ntile;
;     if (more) {
;       const int kn = (it + 1 < na) ? ka0 + (it + 1) * 64 : kb0 + (it + 1 - na) * 64;
;       ALOAD(kn)
;     }
;     ...
;     for (int kh = 0; kh < 2; ++kh) {
;       bf16x8 kf[2][2];
; #pragma unroll
;       for (int t = 0; t < 2; ++t)
; #pragma unroll
;         for (int s2 = 0; s2 < 2; ++s2)
;           kf[t][s2] = *(const bf16x8*)&Ks[(kh * 32 + t * 16 + r) * 64 + (((s2 * 4 + g) ^ (r & 7)) * 8)];
.LBB0_882:
	s_add_i32 s54, s50, 1
	s_cmp_lt_i32 s54, s24
	s_cselect_b64 s[48:49], -1, 0
	s_waitcnt lgkmcnt(0)
	s_barrier
	s_add_i32 s98, s2, 0xffffe000
	s_and_b32 s98, s98, 0x2000
	v_lshl_add_u32 v98, s98, 1, v196
	v_add_u32_e32 v198, v98, v191
	v_add_u32_e32 v197, v98, v192
	ds_read_b128 v[90:93], v198
	ds_read_b128 v[94:97], v198 offset:2048
	ds_read_b128 v[98:101], v197
	ds_read_b128 v[102:105], v197 offset:2048
	s_cmp_ge_i32 s54, s24
	s_cbranch_scc1 .LBB0_884
	s_cmp_lt_i32 s54, s63
	s_cselect_b32 s51, 0, s63
	s_cselect_b32 s52, s64, 0x800
	s_lshl_b32 s51, s51, 6
	s_sub_i32 s51, s52, s51
	s_add_i32 s52, s45, s51
	s_ashr_i32 s53, s52, 31
	s_lshl_b64 s[56:57], s[52:53], 7
	s_waitcnt vmcnt(1)
	v_lshl_add_u64 v[50:51], v[166:167], 0, s[56:57]
	s_waitcnt vmcnt(0)
	v_lshl_add_u64 v[54:55], s[52:53], 1, v[168:169]
	global_load_dwordx4 v[50:53], v[50:51], off
	s_nop 0
	global_load_dwordx4 v[54:57], v[54:55], off

; template <int MODE> ...
;     ...
;     const bool more = it + 1 < ntile;
;     if (more) {
;       const int kn = (it + 1 < na) ? ka0 + (it + 1) * 64 : kb0 + (it + 1 - na) * 64;
;       ALOAD(kn)
;     }
;     bool skip = false;
;     if (masked) {
;       const int qlo = qtok0 + __builtin_amdgcn_readfirstlane(w) * 32;
;       skip = (kt0 > qlo + 31 + 128) || (kt0 + 63 < qlo - 128);
;     }
;     if (!skip) {
.LBB0_886:
	s_waitcnt lgkmcnt(0)
	s_andn2_b64 vcc, exec, s[48:49]
	s_cbranch_vccnz .LBB0_894

; #define MFMA(a, b, c) __builtin_amdgcn_mfma_f32_16x16x32_bf16((a), (b), (c), 0, 0, 0)
; template <int MODE> ...
;     ...
;     for (int kh = 0; kh < 2; ++kh) {
;       bf16x8 kf[2][2];
; #pragma unroll
;       for (int t = 0; t < 2; ++t)
; #pragma unroll
;         for (int s2 = 0; s2 < 2; ++s2)
;           kf[t][s2] = *(const bf16x8*)&Ks[(kh * 32 + t * 16 + r) * 64 + (((s2 * 4 + g) ^ (r & 7)) * 8)];
; #pragma unroll
;       for (int tt = 0; tt < 2; ++tt)
; #pragma unroll
;         for (int hh = 0; hh < 2; ++hh) {
;           f32x4 s0 = zero4(), s1 = zero4();
;           if constexpr (MODE == 0) {
;             s0 = MFMA(kf[0][0], qf[tt][hh][0], s0);
;             s1 = MFMA(kf[1][0], qf[tt][hh][0], s1);
;             s0 = MFMA(kf[0][1], qf[tt][hh][1], s0);
;             s1 = MFMA(kf[1][1], qf[tt][hh][1], s1);
;           } else {
;             s0 = MFMA(kf[0][hh], qf[tt][hh][0], s0);
;             s1 = MFMA(kf[1][hh], qf[tt][hh][0], s1);
;           }
;           S[kh][tt][hh][0] = s0;
;           S[kh][tt][hh][1] = s1;
;         }
;     }
;     if (masked) {
; #pragma unroll
;       for (int kh = 0; kh < 2; ++kh)
; #pragma unroll
;         for (int tt = 0; tt < 2; ++tt) {
;           const int qpos = qtok0 + w * 32 + tt * 16 + r;
;           const int kp0 = kt0 + kh * 32 + g * 8;
; #pragma unroll
;           for (int t = 0; t < 2; ++t)
; #pragma unroll
;             for (int j = 0; j < 4; ++j) {
;               int d = kp0 + t * 4 + j - qpos;
;               d = d < 0 ? -d : d;
;               if (d > 128) { S[kh][tt][0][t][j] = -INFINITY; S[kh][tt][1][t][j] = -INFINITY; }
;             }
;         }
.LBB0_889:
	s_waitcnt lgkmcnt(3)
	v_mfma_f32_16x16x32_bf16 v[142:145], v[90:93], v[18:21], 0
	ds_read_b128 v[174:177], v197 offset:4096
	ds_read_b128 v[178:181], v197 offset:6144
	s_andn2_b64 vcc, exec, s[50:51]
	s_waitcnt lgkmcnt(4)
	v_mfma_f32_16x16x32_bf16 v[138:141], v[94:97], v[18:21], 0
	s_waitcnt lgkmcnt(3)
	v_mfma_f32_16x16x32_bf16 v[126:129], v[98:101], v[22:25], 0
	s_waitcnt lgkmcnt(2)
	v_mfma_f32_16x16x32_bf16 v[122:125], v[102:105], v[22:25], 0
	v_mfma_f32_16x16x32_bf16 v[114:117], v[90:93], v[26:29], 0
	v_mfma_f32_16x16x32_bf16 v[106:109], v[94:97], v[26:29], 0
	v_mfma_f32_16x16x32_bf16 v[94:97], v[98:101], v[30:33], 0
	ds_read_b128 v[98:101], v198 offset:4096
	v_mfma_f32_16x16x32_bf16 v[90:93], v[102:105], v[30:33], 0
	ds_read_b128 v[102:105], v198 offset:6144
	s_waitcnt lgkmcnt(1)
	v_mfma_f32_16x16x32_bf16 v[150:153], v[98:101], v[18:21], 0
	s_waitcnt lgkmcnt(0)
	v_mfma_f32_16x16x32_bf16 v[146:149], v[102:105], v[18:21], 0
	v_mfma_f32_16x16x32_bf16 v[134:137], v[174:177], v[22:25], 0
	v_mfma_f32_16x16x32_bf16 v[130:133], v[178:181], v[22:25], 0
	v_mfma_f32_16x16x32_bf16 v[118:121], v[98:101], v[26:29], 0
	v_mfma_f32_16x16x32_bf16 v[110:113], v[102:105], v[26:29], 0
	v_mfma_f32_16x16x32_bf16 v[102:105], v[174:177], v[30:33], 0
	v_mfma_f32_16x16x32_bf16 v[98:101], v[178:181], v[30:33], 0
	s_cbranch_vccnz .LBB0_891
	s_add_i32 s55, s55, s45
	v_add_u32_e32 v175, s55, v193
	v_subrev_u32_e32 v174, 64, v175
	v_sub_u32_e32 v176, 64, v175
	v_max_i32_e32 v177, v174, v176
	v_mov_b32_e32 v174, s20
	v_mov_b32_e32 v176, s20
	v_cmp_lt_u32_e32 vcc, s95, v177
	s_nop 1
	v_cndmask_b32_e32 v126, v126, v176, vcc
	v_cndmask_b32_e32 v142, v142, v174, vcc
	v_subrev_u32_e32 v174, 63, v175
	v_sub_u32_e32 v176, 63, v175
	v_max_i32_e32 v174, v174, v176
	v_cmp_lt_u32_e32 vcc, s95, v174
	v_subrev_u32_e32 v174, 62, v175
	v_sub_u32_e32 v176, 62, v175
	v_max_i32_e32 v174, v174, v176
	v_cndmask_b32_e32 v127, v127, v194, vcc
	v_cndmask_b32_e32 v143, v143, v194, vcc
	v_cmp_lt_u32_e32 vcc, s95, v174
	v_subrev_u32_e32 v174, 61, v175
	v_sub_u32_e32 v176, 61, v175
	v_max_i32_e32 v174, v174, v176
	v_cndmask_b32_e32 v128, v128, v194, vcc
	v_cndmask_b32_e32 v144, v144, v194, vcc
	v_cmp_lt_u32_e32 vcc, s95, v174
	v_subrev_u32_e32 v174, 60, v175
	v_sub_u32_e32 v176, 60, v175
	v_max_i32_e32 v177, v174, v176
	v_cndmask_b32_e32 v129, v129, v194, vcc
	v_cndmask_b32_e32 v145, v145, v194, vcc
	v_mov_b32_e32 v174, s20
	v_mov_b32_e32 v176, s20
	v_cmp_lt_u32_e32 vcc, s95, v177
	s_nop 1
	v_cndmask_b32_e32 v122, v122, v176, vcc
	v_cndmask_b32_e32 v138, v138, v174, vcc
	v_subrev_u32_e32 v174, 59, v175
	v_sub_u32_e32 v176, 59, v175
	v_max_i32_e32 v174, v174, v176
	v_cmp_lt_u32_e32 vcc, s95, v174
	v_subrev_u32_e32 v174, 58, v175
	v_sub_u32_e32 v176, 58, v175
	v_max_i32_e32 v174, v174, v176
	v_cndmask_b32_e32 v123, v123, v194, vcc
	v_cndmask_b32_e32 v139, v139, v194, vcc
	v_cmp_lt_u32_e32 vcc, s95, v174
	v_subrev_u32_e32 v174, 57, v175
	v_sub_u32_e32 v176, 57, v175
	v_max_i32_e32 v174, v174, v176
	v_cndmask_b32_e32 v124, v124, v194, vcc
	v_cndmask_b32_e32 v140, v140, v194, vcc
	v_cmp_lt_u32_e32 vcc, s95, v174
	v_add_u32_e32 v174, 0xffffffb0, v175
	v_sub_u32_e32 v176, 0x50, v175
	v_max_i32_e32 v177, v174, v176
	v_cndmask_b32_e32 v125, v125, v194, vcc
	v_cndmask_b32_e32 v141, v141, v194, vcc
	v_mov_b32_e32 v174, s20
	v_mov_b32_e32 v176, s20
	v_cmp_lt_u32_e32 vcc, s95, v177
	s_nop 1
	v_cndmask_b32_e32 v94, v94, v176, vcc
	v_cndmask_b32_e32 v114, v114, v174, vcc
	v_add_u32_e32 v174, 0xffffffb1, v175
	v_sub_u32_e32 v176, 0x4f, v175
	v_max_i32_e32 v174, v174, v176
	v_cmp_lt_u32_e32 vcc, s95, v174
	v_add_u32_e32 v174, 0xffffffb2, v175
	v_sub_u32_e32 v176, 0x4e, v175
	v_max_i32_e32 v174, v174, v176
	v_cndmask_b32_e32 v95, v95, v194, vcc
	v_cndmask_b32_e32 v115, v115, v194, vcc
	v_cmp_lt_u32_e32 vcc, s95, v174
	v_add_u32_e32 v174, 0xffffffb3, v175
	v_sub_u32_e32 v176, 0x4d, v175
	v_max_i32_e32 v174, v174, v176
	v_cndmask_b32_e32 v96, v96, v194, vcc
	v_cndmask_b32_e32 v116, v116, v194, vcc
	v_cmp_lt_u32_e32 vcc, s95, v174
	v_add_u32_e32 v174, 0xffffffb4, v175
	v_sub_u32_e32 v176, 0x4c, v175
	v_max_i32_e32 v177, v174, v176
	v_cndmask_b32_e32 v97, v97, v194, vcc
	v_cndmask_b32_e32 v117, v117, v194, vcc
	v_mov_b32_e32 v174, s20
	v_mov_b32_e32 v176, s20
	v_cmp_lt_u32_e32 vcc, s95, v177
	s_nop 1
; template <int MODE> ...
;     ...
;     if (masked) {
; #pragma unroll
;       for (int kh = 0; kh < 2; ++kh)
; #pragma unroll
;         for (int tt = 0; tt < 2; ++tt) {
;           const int qpos = qtok0 + w * 32 + tt * 16 + r;
;           const int kp0 = kt0 + kh * 32 + g * 8;
; #pragma unroll
;           for (int t = 0; t < 2; ++t)
; #pragma unroll
;             for (int j = 0; j < 4; ++j) {
;               int d = kp0 + t * 4 + j - qpos;
;               d = d < 0 ? -d : d;
;               if (d > 128) { S[kh][tt][0][t][j] = -INFINITY; S[kh][tt][1][t][j] = -INFINITY; }
;             }
;         }
	v_cndmask_b32_e32 v90, v90, v176, vcc
	v_cndmask_b32_e32 v106, v106, v174, vcc
	v_add_u32_e32 v174, 0xffffffb5, v175
	v_sub_u32_e32 v176, 0x4b, v175
	v_max_i32_e32 v174, v174, v176
	v_cmp_lt_u32_e32 vcc, s95, v174
	v_add_u32_e32 v174, 0xffffffb6, v175
	v_sub_u32_e32 v176, 0x4a, v175
	v_max_i32_e32 v174, v174, v176
	v_cndmask_b32_e32 v91, v91, v194, vcc
	v_cndmask_b32_e32 v107, v107, v194, vcc
	v_cmp_lt_u32_e32 vcc, s95, v174
	v_add_u32_e32 v174, 0xffffffb7, v175
	v_sub_u32_e32 v176, 0x49, v175
	v_max_i32_e32 v174, v174, v176
	v_cndmask_b32_e32 v92, v92, v194, vcc
	v_cndmask_b32_e32 v108, v108, v194, vcc
	v_cmp_lt_u32_e32 vcc, s95, v174
	v_subrev_u32_e32 v174, 32, v175
	v_sub_u32_e32 v176, 32, v175
	v_max_i32_e32 v177, v174, v176
	v_cndmask_b32_e32 v93, v93, v194, vcc
	v_cndmask_b32_e32 v109, v109, v194, vcc
	v_mov_b32_e32 v174, s20
	v_mov_b32_e32 v176, s20
	v_cmp_lt_u32_e32 vcc, s95, v177
	s_nop 1
	v_cndmask_b32_e32 v150, v150, v174, vcc
	v_cndmask_b32_e32 v134, v134, v176, vcc
	v_subrev_u32_e32 v174, 31, v175
	v_sub_u32_e32 v176, 31, v175
	v_max_i32_e32 v174, v174, v176
	v_cmp_lt_u32_e32 vcc, s95, v174
	v_subrev_u32_e32 v174, 30, v175
	v_sub_u32_e32 v176, 30, v175
	v_max_i32_e32 v174, v174, v176
	v_cndmask_b32_e32 v151, v151, v194, vcc
	v_cndmask_b32_e32 v135, v135, v194, vcc
	v_cmp_lt_u32_e32 vcc, s95, v174
	v_subrev_u32_e32 v174, 29, v175
	v_sub_u32_e32 v176, 29, v175
	v_max_i32_e32 v174, v174, v176
	v_cndmask_b32_e32 v152, v152, v194, vcc
	v_cndmask_b32_e32 v136, v136, v194, vcc
	v_cmp_lt_u32_e32 vcc, s95, v174
	v_subrev_u32_e32 v174, 28, v175
	v_sub_u32_e32 v176, 28, v175
	v_max_i32_e32 v177, v174, v176
	v_cndmask_b32_e32 v153, v153, v194, vcc
	v_cndmask_b32_e32 v137, v137, v194, vcc
	v_mov_b32_e32 v174, s20
	v_mov_b32_e32 v176, s20
	v_cmp_lt_u32_e32 vcc, s95, v177
	s_nop 1
	v_cndmask_b32_e32 v146, v146, v174, vcc
	v_cndmask_b32_e32 v130, v130, v176, vcc
	v_subrev_u32_e32 v174, 27, v175
	v_sub_u32_e32 v176, 27, v175
	v_max_i32_e32 v174, v174, v176
	v_cmp_lt_u32_e32 vcc, s95, v174
	v_subrev_u32_e32 v174, 26, v175
	v_sub_u32_e32 v176, 26, v175
	v_max_i32_e32 v174, v174, v176
	v_cndmask_b32_e32 v147, v147, v194, vcc
	v_cndmask_b32_e32 v131, v131, v194, vcc
	v_cmp_lt_u32_e32 vcc, s95, v174
	v_subrev_u32_e32 v174, 25, v175
	v_sub_u32_e32 v176, 25, v175
	v_max_i32_e32 v174, v174, v176
	v_cndmask_b32_e32 v148, v148, v194, vcc
	v_cndmask_b32_e32 v132, v132, v194, vcc
	v_cmp_lt_u32_e32 vcc, s95, v174
	v_subrev_u32_e32 v174, 48, v175
	v_sub_u32_e32 v176, 48, v175
	v_max_i32_e32 v177, v174, v176
	v_cndmask_b32_e32 v149, v149, v194, vcc
	v_cndmask_b32_e32 v133, v133, v194, vcc
	v_mov_b32_e32 v174, s20
	v_mov_b32_e32 v176, s20
	v_cmp_lt_u32_e32 vcc, s95, v177
	s_nop 1
	v_cndmask_b32_e32 v118, v118, v174, vcc
	v_cndmask_b32_e32 v102, v102, v176, vcc
	v_subrev_u32_e32 v174, 47, v175
	v_sub_u32_e32 v176, 47, v175
	v_max_i32_e32 v174, v174, v176
	v_cmp_lt_u32_e32 vcc, s95, v174
	v_subrev_u32_e32 v174, 46, v175
	v_sub_u32_e32 v176, 46, v175
	v_max_i32_e32 v174, v174, v176
	v_cndmask_b32_e32 v119, v119, v194, vcc
	v_cndmask_b32_e32 v103, v103, v194, vcc
	v_cmp_lt_u32_e32 vcc, s95, v174
	v_subrev_u32_e32 v174, 45, v175
	v_sub_u32_e32 v176, 45, v175
	v_max_i32_e32 v174, v174, v176
	v_cndmask_b32_e32 v120, v120, v194, vcc
	v_cndmask_b32_e32 v104, v104, v194, vcc
	v_cmp_lt_u32_e32 vcc, s95, v174
	v_subrev_u32_e32 v174, 44, v175
	v_sub_u32_e32 v176, 44, v175
	v_max_i32_e32 v177, v174, v176
	v_cndmask_b32_e32 v121, v121, v194, vcc
	v_cndmask_b32_e32 v105, v105, v194, vcc
	v_mov_b32_e32 v174, s20
	v_mov_b32_e32 v176, s20
	v_cmp_lt_u32_e32 vcc, s95, v177
	s_nop 1
	v_cndmask_b32_e32 v110, v110, v174, vcc
	v_cndmask_b32_e32 v98, v98, v176, vcc
	v_subrev_u32_e32 v174, 43, v175
	v_sub_u32_e32 v176, 43, v175
	v_max_i32_e32 v174, v174, v176
	v_cmp_lt_u32_e32 vcc, s95, v174
	v_subrev_u32_e32 v174, 42, v175
	v_sub_u32_e32 v176, 42, v175
	v_max_i32_e32 v174, v174, v176
	v_cndmask_b32_e32 v111, v111, v194, vcc
	v_cndmask_b32_e32 v99, v99, v194, vcc
	v_cmp_lt_u32_e32 vcc, s95, v174
	v_subrev_u32_e32 v174, 41, v175
	v_sub_u32_e32 v175, 41, v175
	v_max_i32_e32 v174, v174, v175
	v_cndmask_b32_e32 v112, v112, v194, vcc
	v_cndmask_b32_e32 v100, v100, v194, vcc
	v_cmp_lt_u32_e32 vcc, s95, v174
	s_nop 1
	v_cndmask_b32_e32 v113, v113, v194, vcc
	v_cndmask_b32_e32 v101, v101, v194, vcc
